# A3 (A3a/b/c) hand-scheduled: each fragment read once (Y shared by both tiles, TT/NRB/VT kept in registers across sub-stages), reads up front with counted lgkmcnt, independent reads issued before the p
# speedup vs baseline: 1.0183x; 1.0005x over previous
; #define LAS __attribute__((address_space(3)))
; __device__ __forceinline__ void st4_lds(LAS unsigned char* p, f32x4 v) { v2u w; w.x = pk2(v[0], v[1]); w.y = pk2(v[2], v[3]); *(LAS v2u*)p = w; }
; __device__ __forceinline__ void st4_g(bf16* p, f32x4 v) { v2u w; w.x = pk2(v[0], v[1]); w.y = pk2(v[2], v[3]); *(GAS v2u*)p = w; }
; __device__ __forceinline__ f32x4 ld4_lds(const LAS unsigned char* p) { const v2u w = *(const LAS v2u*)p; return (f32x4){bflo(w.x), bfhi(w.x), bflo(w.y), bfhi(w.y)}; }
; #define LBAR() asm volatile("s_waitcnt lgkmcnt(0)\n\ts_barrier" ::: "memory")
; __device__ __forceinline__ void rwkv_chunk_group(Frame& F, int bc, unsigned long long& tsub) {
;     ...
; #pragma unroll
;     for (int q = 0; q < 2; ++q) { const int tw = 2 * w + q, p0 = 16 * (tw >> 2), q0 = 16 * (tw & 3); const int o = (p0 + fr) * LD + (q0 + 4 * fq) * 2;
;         const f32x4 ap = mm_tile(L + L_TT, LD, q0, L + L_ATT, LD, p0, 2, Z4, fr, fq);
;         const f32x4 w1 = mm_tile(L + L_NAK, LD, q0, L + L_VT, LD, p0, 2, Z4, fr, fq);
;         st4_lds(L + L_APT + o, ap); st4_lds(L + L_W1T + o, w1); }
;     LBAR();
;     {
;         bf16* RPp = (bf16*)(F.ws + WS_RP) + (size_t)item * 4096; bf16* PTp = (bf16*)(F.ws + WS_PT) + (size_t)item * 4096;
; #pragma unroll
;         for (int q = 0; q < 2; ++q) { const int tw = 2 * w + q, p0 = 16 * (tw >> 2), q0 = 16 * (tw & 3); const int p = p0 + fr; const int o = p * LD + (q0 + 4 * fq) * 2;
;             const f32x4 u0 = mm_tile(L + L_TT, LD, q0, L + L_W1T, LD, p0, 2, Z4, fr, fq);
;             const f32x4 rp = mm_tile(L + L_APT, LD, q0, L + L_NRB, LD, p0, 2, ld4_lds(L + L_RT + o), fr, fq);
;             f32x4 pt = mm_tile(L + L_APT, LD, q0, L + L_BH, LD, p0, 2, Z4, fr, fq);
;             const float wc = *(const LAS float*)(L + L_WC + p * 4);
; #pragma unroll
;             for (int v = 0; v < 4; ++v) if (p == q0 + 4 * fq + v) pt[v] += wc;
;             st4_lds(L + L_U0T + o, u0);
;             st4_g(RPp + p * 64 + q0 + 4 * fq, rp); st4_g(PTp + ((p0 >> 4) * 2 + (q0 >> 5)) * 512 + fr * 32 + (q0 & 16) + 4 * fq, pt); }
;     }
.LBB0_1411:
	v_add_u32_e32 v130, v108, v110
	v_add_u32_e32 v131, v108, v128
	v_add_u32_e32 v133, v109, v110
	v_add_u32_e32 v148, v109, v128
	s_lshl_b64 s[64:65], s[72:73], 1
	s_mov_b32 s77, s95
	s_mov_b32 s93, s95
	ds_read_b128 v[174:177], v130
	ds_read_b128 v[80:83], v107 offset:36864
	ds_read_b128 v[88:91], v133
	ds_read_b128 v[190:193], v107 offset:46080
	ds_read_b128 v[182:185], v131
	ds_read_b128 v[96:99], v148
	ds_read_b128 v[178:181], v130 offset:64
	ds_read_b128 v[84:87], v107 offset:36928
	ds_read_b128 v[92:95], v133 offset:64
	ds_read_b128 v[194:197], v107 offset:46144
	ds_read_b128 v[186:189], v131 offset:64
	ds_read_b128 v[100:103], v148 offset:64
	s_waitcnt lgkmcnt(10)
	v_mfma_f32_16x16x32_bf16 v[36:39], v[174:177], v[80:83], 0
	s_waitcnt lgkmcnt(8)
	v_mfma_f32_16x16x32_bf16 v[40:43], v[88:91], v[190:193], 0
	s_waitcnt lgkmcnt(7)
	v_mfma_f32_16x16x32_bf16 v[44:47], v[182:185], v[80:83], 0
	s_waitcnt lgkmcnt(6)
	v_mfma_f32_16x16x32_bf16 v[224:227], v[96:99], v[190:193], 0
	s_waitcnt lgkmcnt(4)
	v_mfma_f32_16x16x32_bf16 v[36:39], v[178:181], v[84:87], v[36:39]
	s_waitcnt lgkmcnt(2)
	v_mfma_f32_16x16x32_bf16 v[40:43], v[92:95], v[194:197], v[40:43]
	s_waitcnt lgkmcnt(1)
	v_mfma_f32_16x16x32_bf16 v[44:47], v[186:189], v[84:87], v[44:47]
	s_waitcnt lgkmcnt(0)
	v_mfma_f32_16x16x32_bf16 v[224:227], v[100:103], v[194:197], v[224:227]
	ds_read_b128 v[228:231], v144
	ds_read_b128 v[232:235], v144 offset:64
	ds_read_b64 v[250:251], v78 offset:27648
	ds_read_b64 v[164:165], v79 offset:27648
	ds_read_b32 v173, v145
	s_nop 7
	v_cvt_pk_bf16_f32 v36, v36, v37
	v_cvt_pk_bf16_f32 v37, v38, v39
	v_cvt_pk_bf16_f32 v38, v40, v41
	v_cvt_pk_bf16_f32 v39, v42, v43
	ds_write2st64_b64 v142, v[36:37], v[38:39] offset1:18
	v_cvt_pk_bf16_f32 v44, v44, v45
	v_cvt_pk_bf16_f32 v45, v46, v47
	v_cvt_pk_bf16_f32 v46, v224, v225
	v_cvt_pk_bf16_f32 v47, v226, v227
	ds_write2st64_b64 v143, v[44:45], v[46:47] offset1:18
	ds_read_b128 v[80:83], v107 offset:55296
	ds_read_b128 v[84:87], v107 offset:55360
	s_waitcnt lgkmcnt(0)
	s_barrier
	ds_read_b128 v[88:91], v107 offset:9216
	ds_read_b128 v[96:99], v76
	ds_read_b128 v[236:239], v77
	ds_read_b128 v[92:95], v107 offset:9280
	ds_read_b128 v[100:103], v76 offset:64
	ds_read_b128 v[242:245], v77 offset:64
	v_lshlrev_b32_e32 v40, 16, v250
	v_and_b32_e32 v41, 0xffff0000, v250
	v_lshlrev_b32_e32 v42, 16, v251
	v_and_b32_e32 v43, 0xffff0000, v251
	v_lshlrev_b32_e32 v246, 16, v164
	v_and_b32_e32 v247, 0xffff0000, v164
	v_lshlrev_b32_e32 v248, 16, v165
	v_and_b32_e32 v249, 0xffff0000, v165
	s_waitcnt lgkmcnt(5)
	v_mfma_f32_16x16x32_bf16 v[36:39], v[174:177], v[88:91], 0
	s_waitcnt lgkmcnt(4)
	v_mfma_f32_16x16x32_bf16 v[40:43], v[96:99], v[228:231], v[40:43]
	v_mfma_f32_16x16x32_bf16 v[44:47], v[96:99], v[80:83], 0
	v_mfma_f32_16x16x32_bf16 v[224:227], v[182:185], v[88:91], 0
	s_waitcnt lgkmcnt(3)
	v_mfma_f32_16x16x32_bf16 v[246:249], v[236:239], v[228:231], v[246:249]
	v_mfma_f32_16x16x32_bf16 v[198:201], v[236:239], v[80:83], 0
	s_waitcnt lgkmcnt(2)
	v_mfma_f32_16x16x32_bf16 v[36:39], v[178:181], v[92:95], v[36:39]
	s_waitcnt lgkmcnt(1)
	v_mfma_f32_16x16x32_bf16 v[40:43], v[100:103], v[232:235], v[40:43]
	v_mfma_f32_16x16x32_bf16 v[44:47], v[100:103], v[84:87], v[44:47]
	v_mfma_f32_16x16x32_bf16 v[224:227], v[186:189], v[92:95], v[224:227]
	s_waitcnt lgkmcnt(0)
	v_mfma_f32_16x16x32_bf16 v[246:249], v[242:245], v[232:235], v[246:249]
	v_mfma_f32_16x16x32_bf16 v[198:201], v[242:245], v[84:87], v[198:201]
	v_lshl_add_u64 v[148:149], v[66:67], 0, s[64:65]
	v_lshl_add_u64 v[150:151], v[74:75], 0, s[64:65]
	v_lshl_add_u64 v[160:161], v[68:69], 0, s[64:65]
	v_lshl_add_u64 v[166:167], v[70:71], 0, s[64:65]
	s_nop 4
	v_cvt_pk_bf16_f32 v36, v36, v37
	v_cvt_pk_bf16_f32 v37, v38, v39
	ds_write_b64 v78, v[36:37] offset:18432
	v_cvt_pk_bf16_f32 v224, v224, v225
	v_cvt_pk_bf16_f32 v225, v226, v227
	ds_write_b64 v79, v[224:225] offset:18432
	ds_read_b128 v[80:83], v146
	ds_read_b128 v[84:87], v146 offset:64
	ds_read_b128 v[96:99], v76 offset:46080
	ds_read_b128 v[174:177], v76 offset:64512
	ds_read_b128 v[182:185], v76 offset:55296
	ds_read_b128 v[100:103], v76 offset:46144
	ds_read_b128 v[178:181], v76 offset:64576
	ds_read_b128 v[186:189], v76 offset:55360
	v_add_f32_e32 v168, v173, v44
	v_cndmask_b32_e64 v44, v44, v168, s[18:19]
	v_add_f32_e32 v168, v173, v45
	v_cndmask_b32_e64 v45, v45, v168, s[20:21]
	v_add_f32_e32 v168, v173, v46
	v_cndmask_b32_e64 v46, v46, v168, s[22:23]
	v_add_f32_e32 v168, v173, v47
	v_cndmask_b32_e64 v47, v47, v168, s[24:25]
	v_add_f32_e32 v168, v173, v198
	v_cndmask_b32_e64 v198, v198, v168, s[26:27]
	v_add_f32_e32 v168, v173, v199
	v_cndmask_b32_e64 v199, v199, v168, s[28:29]
	v_add_f32_e32 v168, v173, v200
	v_cndmask_b32_e64 v200, v200, v168, s[30:31]
	v_add_f32_e32 v168, v173, v201
	v_cndmask_b32_e64 v201, v201, v168, s[34:35]
	v_cvt_pk_bf16_f32 v40, v40, v41
	v_cvt_pk_bf16_f32 v41, v42, v43
	v_lshl_add_u64 v[168:169], v[148:149], 0, s[76:77]
	global_store_dwordx2 v[168:169], v[40:41], off
	v_cvt_pk_bf16_f32 v44, v44, v45
	v_cvt_pk_bf16_f32 v45, v46, v47
	global_store_dwordx2 v[150:151], v[44:45], off
	v_cvt_pk_bf16_f32 v246, v246, v247
	v_cvt_pk_bf16_f32 v247, v248, v249
	v_lshl_add_u64 v[168:169], v[148:149], 0, s[92:93]
	global_store_dwordx2 v[168:169], v[246:247], off
	v_cvt_pk_bf16_f32 v198, v198, v199
	v_cvt_pk_bf16_f32 v199, v200, v201
	global_store_dwordx2 v[150:151], v[198:199], off offset:32
	s_waitcnt lgkmcnt(0)
	s_barrier
; __device__ __forceinline__ void st4_g(bf16* p, f32x4 v) { v2u w; w.x = pk2(v[0], v[1]); w.y = pk2(v[2], v[3]); *(GAS v2u*)p = w; }
; #define LBAR() asm volatile("s_waitcnt lgkmcnt(0)\n\ts_barrier" ::: "memory")
; #define TSUB(k) do { } while (0)
; __device__ __forceinline__ void rwkv_chunk_group(Frame& F, int bc, unsigned long long& tsub) {
;     ...
;     {
;         bf16* Y0p = (bf16*)(F.ws + WS_Y0) + (size_t)item * 4096; bf16* QCp = (bf16*)(F.ws + WS_QC) + (size_t)item * 4096;
; #pragma unroll
;         for (int q = 0; q < 2; ++q) { const int tw = 2 * w + q, p0 = 16 * (tw >> 2), q0 = 16 * (tw & 3); const int p = p0 + fr;
;             f32x4 y0 = mm_tile(L + L_VT, LD, q0, L + L_NRK, LD, p0, 2, Z4, fr, fq);
;             y0 = mm_tile(L + L_U0T, LD, q0, L + L_NRB, LD, p0, 2, y0, fr, fq);
;             f32x4 qc = mm_tile(L + L_KH, LD, q0, L + L_VT, LD, p0, 2, Z4, fr, fq);
;             qc = mm_tile(L + L_BH, LD, q0, L + L_U0T, LD, p0, 2, qc, fr, fq);
;             st4_g(Y0p + p * 64 + q0 + 4 * fq, y0); st4_g(QCp + p * 64 + q0 + 4 * fq, qc); }
;     }
;     LBAR();
;     TSUB(5);
;     }
	ds_read_b128 v[88:91], v107 offset:18432
	ds_read_b128 v[236:239], v76 offset:18432
	ds_read_b128 v[92:95], v107 offset:18496
	ds_read_b128 v[242:245], v76 offset:18496
	ds_read_b128 v[246:249], v77 offset:46080
	ds_read_b128 v[198:201], v77 offset:46144
	v_mfma_f32_16x16x32_bf16 v[36:39], v[96:99], v[80:83], 0
	v_mfma_f32_16x16x32_bf16 v[36:39], v[100:103], v[84:87], v[36:39]
	v_mfma_f32_16x16x32_bf16 v[40:43], v[174:177], v[190:193], 0
	v_mfma_f32_16x16x32_bf16 v[40:43], v[178:181], v[194:197], v[40:43]
	ds_read_b128 v[174:177], v77 offset:64512
	ds_read_b128 v[178:181], v77 offset:64576
	s_waitcnt lgkmcnt(7)
	v_mfma_f32_16x16x32_bf16 v[40:43], v[182:185], v[88:91], v[40:43]
	s_waitcnt lgkmcnt(5)
	v_mfma_f32_16x16x32_bf16 v[40:43], v[186:189], v[92:95], v[40:43]
	ds_read_b128 v[182:185], v77 offset:55296
	ds_read_b128 v[186:189], v77 offset:55360
	v_mfma_f32_16x16x32_bf16 v[36:39], v[236:239], v[228:231], v[36:39]
	s_waitcnt lgkmcnt(6)
	v_mfma_f32_16x16x32_bf16 v[36:39], v[242:245], v[232:235], v[36:39]
	ds_read_b128 v[236:239], v77 offset:18432
	ds_read_b128 v[242:245], v77 offset:18496
	s_waitcnt lgkmcnt(7)
	v_mfma_f32_16x16x32_bf16 v[44:47], v[246:249], v[80:83], 0
	s_waitcnt lgkmcnt(6)
	v_mfma_f32_16x16x32_bf16 v[44:47], v[198:201], v[84:87], v[44:47]
	s_waitcnt lgkmcnt(5)
	v_mfma_f32_16x16x32_bf16 v[224:227], v[174:177], v[190:193], 0
	s_waitcnt lgkmcnt(4)
	v_mfma_f32_16x16x32_bf16 v[224:227], v[178:181], v[194:197], v[224:227]
	s_waitcnt lgkmcnt(3)
	v_mfma_f32_16x16x32_bf16 v[224:227], v[182:185], v[88:91], v[224:227]
	s_waitcnt lgkmcnt(2)
	v_mfma_f32_16x16x32_bf16 v[224:227], v[186:189], v[92:95], v[224:227]
	s_waitcnt lgkmcnt(1)
	v_mfma_f32_16x16x32_bf16 v[44:47], v[236:239], v[228:231], v[44:47]
	s_waitcnt lgkmcnt(0)
	v_mfma_f32_16x16x32_bf16 v[44:47], v[242:245], v[232:235], v[44:47]
	v_cvt_pk_bf16_f32 v36, v36, v37
	v_cvt_pk_bf16_f32 v37, v38, v39
	v_lshl_add_u64 v[168:169], v[160:161], 0, s[76:77]
	global_store_dwordx2 v[168:169], v[36:37], off
	v_cvt_pk_bf16_f32 v40, v40, v41
	v_cvt_pk_bf16_f32 v41, v42, v43
	v_lshl_add_u64 v[168:169], v[166:167], 0, s[76:77]
	global_store_dwordx2 v[168:169], v[40:41], off
	s_nop 7
	v_cvt_pk_bf16_f32 v224, v224, v225
	v_cvt_pk_bf16_f32 v225, v226, v227
	v_lshl_add_u64 v[168:169], v[166:167], 0, s[92:93]
	global_store_dwordx2 v[168:169], v[224:225], off
	v_cvt_pk_bf16_f32 v44, v44, v45
	v_cvt_pk_bf16_f32 v45, v46, v47
	v_lshl_add_u64 v[168:169], v[160:161], 0, s[92:93]
	global_store_dwordx2 v[168:169], v[44:45], off
	s_waitcnt lgkmcnt(0)
	s_barrier
	s_cmp_lg_u32 s12, 8
	s_cbranch_scc0 .LBB0_1392
